# phase 2->3 grid barrier: arrive before the sample in_proj, deferred wait after it
# baseline (speedup 1.0000x reference)
.LBB0_186:
	s_cmp_gt_i32 s93, 3
	s_cbranch_scc0 .Lb2_noarr
	s_waitcnt vmcnt(0)
	s_barrier
	v_writelane_b32 v243, s19, 0
	v_writelane_b32 v243, s21, 1
	v_writelane_b32 v243, s62, 2
	v_writelane_b32 v243, s63, 3
	v_writelane_b32 v243, s72, 4
	v_writelane_b32 v243, s73, 5
	v_writelane_b32 v243, s74, 6
	v_writelane_b32 v243, s75, 7
	s_and_saveexec_b64 s[0:1], s[94:95]
	s_cbranch_execz .LBB0_248
	s_add_i32 s2, 0, 0x24160
	v_mov_b32_e32 v1, s2
	s_waitcnt vmcnt(0) expcnt(0) lgkmcnt(0)
	ds_read_b32 v3, v1
	s_add_i32 s2, 0, 0x24164
	v_mov_b32_e32 v1, s2
	ds_read_b32 v1, v1
	s_waitcnt lgkmcnt(1)
	v_cmp_ne_u32_e32 vcc, 0, v3
	s_cbranch_vccnz .LBB0_212
	v_readlane_b32 s2, v245, 0
	v_readlane_b32 s3, v245, 1
	s_load_dwordx2 s[6:7], s[2:3], 0x4
	s_add_u32 s2, s68, 0x4200
	s_addc_u32 s3, s69, 0
	s_add_u32 s4, s68, 0x4400
	s_addc_u32 s5, s69, 0
	s_add_u32 s10, s68, 0x4500
	s_addc_u32 s11, s69, 0
	s_add_u32 s56, s68, 0x4600
	s_addc_u32 s57, s69, 0
	s_add_u32 s58, s68, 0x4700
	s_addc_u32 s59, s69, 0
	s_add_u32 s60, s68, 0x4800
	s_addc_u32 s61, s69, 0
	s_add_u32 s62, s68, 0x4900
	s_addc_u32 s63, s69, 0
	s_add_u32 s72, s68, 0x4a00
	s_addc_u32 s73, s69, 0
	s_add_u32 s74, s68, 0x4b00
	s_addc_u32 s75, s69, 0
	s_add_u32 s76, s68, 0x4c00
	s_addc_u32 s77, s69, 0
	s_add_u32 s78, s68, 0x4d00
	s_addc_u32 s79, s69, 0
	s_add_u32 s80, s68, 0x4e00
	s_addc_u32 s81, s69, 0
	s_add_u32 s82, s68, 0x4f00
	s_addc_u32 s83, s69, 0
	s_mov_b64 s[16:17], s[84:85]
	s_add_u32 s84, s68, 0x5000
	s_addc_u32 s85, s69, 0
	s_mov_b64 s[20:21], s[88:89]
	s_add_u32 s88, s68, 0x5100
	s_addc_u32 s89, s69, 0
	s_mov_b32 s23, s90
	s_add_u32 s90, s68, 0x5200
	s_mov_b32 s22, s91
	s_addc_u32 s91, s69, 0
	s_mov_b64 s[18:19], s[92:93]
	s_waitcnt lgkmcnt(0)
	s_mul_i32 s6, s6, s33
	s_add_u32 s92, s68, 0x5300
	s_mov_b32 s15, s96
	s_mul_i32 s6, s6, s7
	s_addc_u32 s93, s69, 0
	s_mov_b32 s7, 1
	v_mov_b32_e32 v17, 0
	s_branch .LBB0_200

.LBB0_214:
	s_or_b64 exec, exec, s[10:11]
	v_cvt_f32_u32_e32 v5, v3
	s_waitcnt vmcnt(0)
	v_readfirstlane_b32 s4, v4
	v_sub_u32_e32 v4, 0, v3
	v_rcp_iflag_f32_e32 v5, v5
	v_add_u32_e32 v6, s4, v2
	v_mul_f32_e32 v5, 0x4f7ffffe, v5
	v_cvt_u32_f32_e32 v5, v5
	v_mul_lo_u32 v2, v4, v5
	v_mul_hi_u32 v2, v5, v2
	v_add_u32_e32 v2, v5, v2
	v_mul_hi_u32 v2, v6, v2
	v_mul_lo_u32 v4, v2, v3
	v_sub_u32_e32 v4, v6, v4
	v_add_u32_e32 v5, 1, v2
	v_cmp_ge_u32_e32 vcc, v4, v3
	s_nop 1
	v_cndmask_b32_e32 v2, v2, v5, vcc
	v_sub_u32_e32 v5, v4, v3
	v_cndmask_b32_e32 v4, v4, v5, vcc
	v_add_u32_e32 v5, 1, v2
	v_cmp_ge_u32_e32 vcc, v4, v3
	v_add_u32_e32 v4, 1, v6
	s_nop 0
	v_cndmask_b32_e32 v2, v2, v5, vcc
	v_mul_lo_u32 v5, v3, v2
	v_add_u32_e32 v3, v5, v3
	v_cmp_ne_u32_e32 vcc, v4, v3
	s_and_saveexec_b64 s[4:5], vcc
	s_xor_b64 s[4:5], exec, s[4:5]
	s_cbranch_execz .LBB0_228
	s_waitcnt lgkmcnt(0)
	s_branch .Lb2_defer
	v_mov_b32_e32 v1, 0x2000
	global_load_dword v1, v1, s[2:3] offset:1024 sc1
	s_add_u32 s58, s2, 0x2400
	s_addc_u32 s59, s3, 0
	s_waitcnt vmcnt(0)
	v_cmp_eq_u32_e32 vcc, v1, v2
	s_and_saveexec_b64 s[10:11], vcc
	s_cbranch_execz .LBB0_227
	s_add_u32 s56, s68, 0x4200
	s_addc_u32 s57, s69, 0
	s_mov_b32 s6, 1
	s_mov_b64 s[60:61], 0
	v_mov_b32_e32 v1, 0
	s_branch .LBB0_218

.LBB0_248:
	s_or_b64 exec, exec, s[0:1]
	s_waitcnt lgkmcnt(0)
	s_barrier
	v_readlane_b32 s19, v243, 0
	v_readlane_b32 s21, v243, 1
	v_readlane_b32 s62, v243, 2
	v_readlane_b32 s63, v243, 3
	v_readlane_b32 s72, v243, 4
	v_readlane_b32 s73, v243, 5
	v_readlane_b32 s74, v243, 6
	v_readlane_b32 s75, v243, 7
	s_branch .Lb2_noarr
.Lb2_defer:
	s_add_u32 s58, s2, 0x2400
	s_addc_u32 s59, s3, 0
	v_mov_b32_e32 v1, 0x24200
	v_mov_b32_e32 v4, 1
	v_mov_b32_e32 v5, s58
	v_mov_b32_e32 v6, s59
	ds_write_b32 v1, v4
	ds_write_b32 v1, v2 offset:4
	ds_write_b32 v1, v5 offset:8
	ds_write_b32 v1, v6 offset:12
	s_branch .LBB0_228

.LBB0_195:
	s_cmp_gt_i32 s93, 3
	s_barrier
	s_cbranch_scc0 .LBB0_249
	s_waitcnt vmcnt(0)
	v_mov_b32_e32 v1, 0x24200
	ds_read_b32 v2, v1
	s_waitcnt lgkmcnt(0)
	v_readfirstlane_b32 s6, v2
	s_barrier
	s_cmp_eq_u32 s6, 0
	s_cbranch_scc1 .LBB0_249
	s_and_saveexec_b64 s[4:5], s[94:95]
	s_cbranch_execz .Lb2_wd
	ds_read_b32 v2, v1 offset:8
	s_waitcnt lgkmcnt(0)
	v_readfirstlane_b32 s10, v2
	ds_read_b32 v2, v1 offset:12
	s_waitcnt lgkmcnt(0)
	v_readfirstlane_b32 s11, v2
	ds_read_b32 v2, v1 offset:4
	s_waitcnt lgkmcnt(0)
	v_mov_b32_e32 v4, 0
	ds_write_b32 v1, v4
	s_mov_b32 s6, 0
	s_nop 4

.Lb2_wd:
	s_or_b64 exec, exec, s[4:5]
	s_waitcnt lgkmcnt(0)
	s_barrier
.LBB0_249:
	v_and_b32_e32 v230, 48, v0
	v_sub_u32_e32 v230, 0, v230
	v_ashrrev_i32_e32 v231, 31, v230
	s_add_u32 s58, s68, 0x80000
	s_addc_u32 s59, s69, 0
	s_add_u32 s62, s68, 0x2500000
	s_addc_u32 s63, s69, 0
	s_add_u32 s0, s68, 0x2540000
	s_addc_u32 s1, s69, 0
	v_writelane_b32 v245, s0, 36
	s_nop 1
	v_writelane_b32 v245, s1, 37
	s_add_u32 s0, s68, 0x2580000
	s_addc_u32 s1, s69, 0
	v_writelane_b32 v245, s0, 38
	s_nop 1
	v_writelane_b32 v245, s1, 39
	s_add_u32 s0, s68, 0x8c00000
	s_addc_u32 s1, s69, 0
	v_writelane_b32 v245, s0, 40
	s_nop 1
	v_writelane_b32 v245, s1, 41
	s_add_u32 s0, s68, 0xa000000
	s_addc_u32 s1, s69, 0
	v_writelane_b32 v245, s0, 42
	s_nop 1
	v_writelane_b32 v245, s1, 43
	s_add_u32 s0, s68, 0xb400000
	s_addc_u32 s1, s69, 0
	v_writelane_b32 v245, s0, 44
	s_nop 1
	v_writelane_b32 v245, s1, 45
	s_add_u32 s0, s68, 0xc800000
	s_addc_u32 s1, s69, 0
	s_add_u32 s56, s68, 0xdc00000
	s_addc_u32 s57, s69, 0
	v_writelane_b32 v245, s0, 46
	s_cmp_lt_i32 s92, 4
	s_nop 0
	v_writelane_b32 v245, s1, 47
	s_cselect_b64 s[0:1], -1, 0
	s_cmp_gt_i32 s93, 3
	s_cselect_b64 s[2:3], -1, 0
	s_and_b64 s[0:1], s[0:1], s[2:3]
	s_andn2_b64 vcc, exec, s[0:1]
	s_cbranch_vccnz .LBB0_508
	s_sub_i32 s15, s33, 32
	s_cmp_ge_i32 s12, s15
	s_mov_b64 s[0:1], -1
	s_cbranch_scc0 .LBB0_326
	s_sub_i32 s0, s12, s15
	s_and_b32 s0, s0, -8
	s_and_b32 s1, s12, 7
	s_or_b32 s0, s0, s1
	s_addk_i32 s0, 0x80
	s_mul_i32 s2, s15, 3
	s_ashr_i32 s3, s0, 31
	s_mul_hi_i32 s1, s15, 3
	s_add_u32 s0, s2, s0
	s_addc_u32 s1, s1, s3
	s_waitcnt vmcnt(1)
	v_mov_b64_e32 v[2:3], 0x37f
	s_waitcnt vmcnt(0)
	v_mov_b32_e32 v13, v0
	v_cmp_gt_i64_e32 vcc, s[0:1], v[2:3]
	s_nop 0
	v_readfirstlane_b32 s6, v13
	s_cbranch_vccnz .LBB0_325
	v_lshlrev_b32_e32 v1, 4, v13
	v_add_u32_e32 v2, 0x2000, v1
	v_ashrrev_i32_e32 v3, 31, v2
	v_lshrrev_b32_e32 v3, 22, v3
	v_add_u32_e32 v3, v2, v3
	v_ashrrev_i32_e32 v10, 10, v3
	v_mul_i32_i24_e32 v3, 0x400, v10
	v_sub_u32_e32 v2, v2, v3
	v_lshrrev_b32_e32 v3, 4, v2
	v_bitop3_b32 v2, v3, v2, 32 bitop3:0x6c
	v_ashrrev_i32_e32 v3, 31, v2
	v_lshrrev_b32_e32 v3, 26, v3
	v_add_u32_e32 v3, v2, v3
	v_lshlrev_b32_e32 v4, 3, v10
	v_ashrrev_i32_e32 v11, 6, v3
	v_and_b32_e32 v4, -16, v4
	v_add_u32_e32 v4, v11, v4
	v_and_b32_e32 v5, 3, v11
	s_mov_b32 s1, 0x1fffe0
	v_lshrrev_b32_e32 v6, 2, v4
	v_lshlrev_b32_e32 v7, 1, v4
	v_and_b32_e32 v3, 0xc0, v3
	v_and_or_b32 v5, v4, s1, v5
	v_and_b32_e32 v6, 4, v6
	v_and_b32_e32 v7, 24, v7
	v_sub_u32_e32 v2, v2, v3
	v_mov_b32_e32 v3, 1
	v_or3_b32 v5, v5, v6, v7
	v_lshlrev_b32_e32 v6, 5, v10
	v_ashrrev_i16_sdwa v2, v3, sext(v2) dst_sel:DWORD dst_unused:UNUSED_PAD src0_sel:DWORD src1_sel:BYTE_0
	v_and_b32_e32 v6, 32, v6
	v_bfe_i32 v12, v2, 0, 16
	v_add_lshl_u32 v2, v6, v12, 1
	v_lshl_add_u32 v130, v5, 11, v2
	v_lshl_add_u32 v132, v4, 11, v2
	v_bfe_i32 v2, v13, 27, 1
	v_lshrrev_b32_e32 v2, 22, v2
	v_add_u32_e32 v2, v1, v2
	v_and_b32_e32 v2, 0xfffffc00, v2
	v_sub_u32_e32 v1, v1, v2
	v_lshrrev_b32_e32 v2, 4, v1
	v_ashrrev_i32_e32 v4, 31, v13
	v_bitop3_b32 v1, v2, v1, 32 bitop3:0x6c
	v_lshrrev_b32_e32 v4, 26, v4
	v_ashrrev_i32_e32 v2, 31, v1
	v_add_u32_e32 v4, v13, v4
	v_lshrrev_b32_e32 v2, 26, v2
	v_ashrrev_i32_e32 v15, 6, v4
	v_add_u32_e32 v2, v1, v2
	v_lshlrev_b32_e32 v4, 3, v15
	v_ashrrev_i32_e32 v14, 6, v2
	v_and_b32_e32 v4, -16, v4
	v_add_u32_e32 v4, v14, v4
	v_and_b32_e32 v5, 3, v14
	v_and_or_b32 v5, v4, s1, v5
	s_ashr_i32 s1, s0, 31
	s_lshr_b32 s1, s1, 29
	s_add_i32 s1, s0, s1
	s_ashr_i32 s17, s6, 6
	s_ashr_i32 s2, s1, 3
	s_and_b32 s1, s1, -8
	s_mov_b64 s[38:39], s[62:63]
	s_ashr_i32 s18, s6, 8
	s_lshl_b32 s62, s17, 10
	s_sub_i32 s0, s0, s1
	s_cmp_lt_i32 s0, 0
	s_movk_i32 s1, 0x71
	s_cselect_b32 s1, s1, 0x70
	s_mul_i32 s0, s0, s1
	s_add_i32 s0, s0, s2
	s_mul_hi_i32 s1, s0, 0x92492493
	s_add_i32 s1, s1, s0
	s_lshr_b32 s2, s1, 31
	s_ashr_i32 s1, s1, 6
	s_add_i32 s1, s1, s2
	s_lshl_b32 s2, s1, 3
	v_and_b32_e32 v2, 0xc0, v2
	s_sub_i32 s3, 64, s2
	v_sub_u32_e32 v1, v1, v2
	s_min_i32 s3, s3, 8
	v_ashrrev_i16_sdwa v1, v3, sext(v1) dst_sel:DWORD dst_unused:UNUSED_PAD src0_sel:DWORD src1_sel:BYTE_0
	s_abs_i32 s4, s3
	v_bfe_i32 v16, v1, 0, 16
	v_cvt_f32_u32_e32 v1, s4
	s_sub_i32 s7, 0, s4
	s_mulk_i32 s1, 0x70
	s_sub_i32 s1, s0, s1
	v_rcp_iflag_f32_e32 v1, v1
	s_abs_i32 s5, s1
	s_xor_b32 s0, s1, s3
	s_ashr_i32 s0, s0, 31
	v_mul_f32_e32 v1, 0x4f7ffffe, v1
	v_cvt_u32_f32_e32 v1, v1
	v_lshrrev_b32_e32 v6, 2, v4
	v_lshlrev_b32_e32 v7, 1, v4
	v_and_b32_e32 v6, 4, v6
	v_readfirstlane_b32 s10, v1
	s_mul_i32 s7, s7, s10
	s_mul_hi_u32 s7, s10, s7
	s_add_i32 s10, s10, s7
	s_mul_hi_u32 s7, s5, s10
	s_mul_i32 s10, s7, s4
	s_sub_i32 s5, s5, s10
	s_add_i32 s10, s7, 1
	s_sub_i32 s11, s5, s4
	s_cmp_ge_u32 s5, s4
	s_cselect_b32 s7, s10, s7
	s_cselect_b32 s5, s11, s5
	s_add_i32 s10, s7, 1
	s_cmp_ge_u32 s5, s4
	s_cselect_b32 s4, s10, s7
	s_xor_b32 s4, s4, s0
	s_sub_i32 s0, s4, s0
	s_mul_i32 s3, s0, s3
	s_sub_i32 s1, s1, s3
	s_add_i32 s2, s2, s1
	v_and_b32_e32 v7, 24, v7
	s_ashr_i32 s3, s2, 31
	s_ashr_i32 s1, s0, 31
	v_or3_b32 v5, v5, v6, v7
	v_lshlrev_b32_e32 v6, 5, v15
	s_lshl_b64 s[74:75], s[2:3], 19
	s_lshl_b64 s[78:79], s[0:1], 19
	v_and_b32_e32 v6, 32, v6
	s_add_u32 s4, s8, s78
	v_add_lshl_u32 v2, v6, v16, 1
	s_addc_u32 s5, s9, s79
	s_add_i32 s1, s62, 0
	v_lshl_add_u32 v134, v5, 11, v2
	s_add_i32 m0, s1, 0x10000
	v_lshl_add_u32 v136, v4, 11, v2
	global_load_lds_dwordx4 v134, s[4:5]
	s_add_i32 m0, s1, 0x12000
	s_add_u32 s10, s4, 0x40000
	global_load_lds_dwordx4 v130, s[4:5]
	s_addc_u32 s11, s5, 0
	s_add_i32 m0, s1, 0x14000
	v_mov_b32_e32 v135, 0
	global_load_lds_dwordx4 v134, s[10:11]
	s_add_i32 m0, s1, 0x16000
	v_mov_b32_e32 v131, v135
	global_load_lds_dwordx4 v130, s[10:11]
	s_add_u32 s10, s52, s74
	s_addc_u32 s11, s53, s75
	s_add_i32 s7, s1, 0x2000
	s_mov_b32 m0, s1
	s_add_u32 s24, s10, 0x40000
	global_load_lds_dwordx4 v136, s[10:11]
	s_mov_b32 m0, s7
	s_addc_u32 s25, s11, 0
	s_add_i32 s13, s1, 0x4000
	global_load_lds_dwordx4 v132, s[10:11]
	s_mov_b32 m0, s13
	s_add_i32 s16, s1, 0x6000
	global_load_lds_dwordx4 v136, s[24:25]
	s_mov_b32 m0, s16
	v_mov_b32_e32 v137, v135
	global_load_lds_dwordx4 v132, s[24:25]
	v_mov_b32_e32 v133, v135
	s_mov_b64 s[36:37], s[84:85]
	v_lshl_add_u64 v[8:9], s[4:5], 0, v[134:135]
	v_lshl_add_u64 v[6:7], s[4:5], 0, v[130:131]
	v_lshl_add_u64 v[4:5], s[10:11], 0, v[136:137]
	s_cmp_lg_u32 s18, 1
	v_lshl_add_u64 v[2:3], s[10:11], 0, v[132:133]
	s_cbranch_scc1 .LBB0_254
	s_barrier
